# GLA pass 1 walks its units in reverse (most recently touched gate/key/value rows first)
# speedup vs baseline: 1.0072x; 1.0011x over previous
.Lprio_b:
	s_load_dwordx4 s[8:11], s[0:1], 0xa0
	v_mov_b32_e32 v172, v240
	v_mov_b32_e32 v3, 0x100
	v_mov_b32_e32 v149, 0
	s_movk_i32 s30, 0x1000
	s_waitcnt lgkmcnt(0)
	v_mov_b32_e32 v0, s10
	v_mov_b32_e32 v1, s11
	v_mov_b32_e32 v16, s24
	v_readfirstlane_b32 s6, v0
	v_mov_b32_e32 v0, s2
	v_readfirstlane_b32 s7, v1
	v_ashrrev_i32_e32 v1, 2, v172
	v_readfirstlane_b32 s28, v0
	s_sub_i32 s28, 0x5ff, s28
	s_and_b32 s16, s28, 1
	v_and_b32_e32 v1, 0xffffffc0, v1
	v_lshrrev_b32_e32 v2, 1, v172
	v_and_b32_e32 v0, 31, v172
	v_lshl_add_u32 v1, s16, 7, v1
	v_and_b32_e32 v2, 32, v2
	v_or3_b32 v10, v2, v0, v1
	v_and_b32_e32 v0, 0x80, v172
	s_add_u32 s12, s6, 0x3790000
	v_mov_b32_e32 v2, 0x4500
	v_cmp_eq_u32_e32 vcc, 0, v0
	s_addc_u32 s13, s7, 0
	v_ashrrev_i32_e32 v11, 31, v10
	v_cndmask_b32_e32 v148, v2, v3, vcc
	v_lshl_add_u64 v[2:3], s[12:13], 0, v[148:149]
	v_lshlrev_b32_e32 v0, 8, v172
	v_lshl_add_u64 v[2:3], v[10:11], 2, v[2:3]
	v_and_b32_e32 v148, 0x2000, v0
	v_lshl_add_u64 v[12:13], v[2:3], 0, v[148:149]
	v_add_co_u32_e64 v14, s[4:5], s30, v12
	v_mov_b32_e32 v0, 0x2140
	s_nop 0
	v_addc_co_u32_e64 v15, s[4:5], 0, v13, s[4:5]
	global_load_dword v2, v[12:13], off
	global_load_dword v3, v[12:13], off offset:1024
	global_load_dword v4, v[12:13], off offset:2048
	global_load_dword v5, v[12:13], off offset:3072
	global_load_dword v6, v[14:15], off
	global_load_dword v7, v[14:15], off offset:1024
	global_load_dword v8, v[14:15], off offset:2048
	global_load_dword v9, v[14:15], off offset:3072
	v_mov_b32_e32 v11, 0x1040
	v_cndmask_b32_e32 v0, v0, v11, vcc
	v_add_u32_e32 v10, v10, v0
	v_ashrrev_i32_e32 v11, 31, v10
	v_lshl_add_u64 v[10:11], v[10:11], 2, s[12:13]
	global_load_dword v0, v[10:11], off
	v_mov_b32_e32 v10, s9
	v_mov_b32_e32 v11, s8
	v_readfirstlane_b32 s31, v16
	s_cmpk_lt_i32 s28, 0x600
	v_readfirstlane_b32 s8, v11
	v_readfirstlane_b32 s9, v10
	s_cbranch_scc0 .LBB0_726
	s_lshl_b32 s4, s28, 5
	s_and_b32 s17, s4, 0xffffffc0
	v_lshrrev_b32_e32 v11, 2, v172
	s_add_u32 s10, s6, 0xe000000
	s_addc_u32 s11, s7, 0
	v_and_or_b32 v12, v11, 48, s17
	s_add_u32 s12, s6, 0xf800000
	v_and_or_b32 v10, v172, 63, v1
	v_ashrrev_i32_e32 v13, 31, v12
	s_addc_u32 s13, s7, 0
	v_lshlrev_b64 v[12:13], 9, v[12:13]
	v_ashrrev_i32_e32 v11, 31, v10
	v_lshl_add_u64 v[14:15], s[12:13], 0, v[12:13]
	v_lshlrev_b64 v[10:11], 1, v[10:11]
	v_lshl_add_u64 v[14:15], v[14:15], 0, v[10:11]
	v_lshl_add_u64 v[12:13], s[10:11], 0, v[12:13]
	v_lshl_add_u64 v[10:11], v[12:13], 0, v[10:11]
	v_add_co_u32_e32 v12, vcc, s30, v14
	global_load_ushort v1, v[14:15], off
	global_load_ushort v16, v[14:15], off offset:512
	global_load_ushort v17, v[14:15], off offset:1024
	global_load_ushort v18, v[14:15], off offset:1536
	global_load_ushort v19, v[14:15], off offset:2048
	global_load_ushort v20, v[14:15], off offset:2560
	global_load_ushort v21, v[14:15], off offset:3072
	global_load_ushort v22, v[14:15], off offset:3584
	global_load_ushort v23, v[10:11], off
	global_load_ushort v24, v[10:11], off offset:512
	global_load_ushort v25, v[10:11], off offset:1024
	global_load_ushort v26, v[10:11], off offset:1536
	global_load_ushort v27, v[10:11], off offset:2048
	global_load_ushort v28, v[10:11], off offset:2560
	global_load_ushort v29, v[10:11], off offset:3072
	global_load_ushort v30, v[10:11], off offset:3584
	v_addc_co_u32_e32 v13, vcc, 0, v15, vcc
	v_add_co_u32_e32 v10, vcc, s30, v10
	s_add_u32 s33, s6, 0x11000000
	s_nop 0
	v_addc_co_u32_e32 v11, vcc, 0, v11, vcc
	global_load_ushort v31, v[12:13], off
	global_load_ushort v32, v[12:13], off offset:512
	global_load_ushort v33, v[12:13], off offset:1024
	global_load_ushort v34, v[12:13], off offset:1536
	global_load_ushort v35, v[12:13], off offset:2048
	global_load_ushort v36, v[12:13], off offset:2560
	global_load_ushort v37, v[12:13], off offset:3072
	global_load_ushort v38, v[12:13], off offset:3584
	global_load_ushort v39, v[10:11], off
	global_load_ushort v40, v[10:11], off offset:512
	global_load_ushort v41, v[10:11], off offset:1024
	global_load_ushort v42, v[10:11], off offset:1536
	global_load_ushort v43, v[10:11], off offset:2048
	global_load_ushort v44, v[10:11], off offset:2560
	global_load_ushort v45, v[10:11], off offset:3072
	global_load_ushort v46, v[10:11], off offset:3584
	v_ashrrev_i32_e32 v10, 3, v172
	s_addc_u32 s34, s7, 0
	v_add_u32_e32 v10, s17, v10
	s_add_u32 s14, s6, 0x17000000
	v_ashrrev_i32_e32 v11, 31, v10
	s_addc_u32 s15, s7, 0
	v_lshlrev_b64 v[10:11], 7, v[10:11]
	v_lshlrev_b32_e32 v12, 4, v172
	s_lshl_b32 s4, s16, 9
	v_ashrrev_i32_e32 v14, 5, v172
	v_lshl_add_u64 v[10:11], s[14:15], 0, v[10:11]
	v_and_b32_e32 v148, 0x70, v12
	s_add_u32 s4, s33, s4
	v_add_u32_e32 v14, s17, v14
	v_lshl_add_u64 v[10:11], v[10:11], 0, v[148:149]
	s_addc_u32 s5, s34, 0
	v_and_b32_e32 v148, 0x1f0, v12
	v_ashrrev_i32_e32 v15, 31, v14
	v_lshl_add_u64 v[12:13], s[4:5], 0, v[148:149]
	v_lshlrev_b64 v[14:15], 10, v[14:15]
	v_lshl_add_u64 v[14:15], v[12:13], 0, v[14:15]
	global_load_dwordx4 v[72:75], v[10:11], off
	global_load_dwordx4 v[76:79], v[14:15], off
	v_add_u32_e32 v10, 0x200, v172
	v_ashrrev_i32_e32 v10, 5, v10
	v_add_u32_e32 v14, 0x400, v172
	v_add_u32_e32 v10, s17, v10
	v_ashrrev_i32_e32 v14, 5, v14
	v_ashrrev_i32_e32 v11, 31, v10
	v_add_u32_e32 v14, s17, v14
	v_lshlrev_b64 v[10:11], 10, v[10:11]
	v_ashrrev_i32_e32 v15, 31, v14
	v_lshl_add_u64 v[10:11], v[12:13], 0, v[10:11]
	v_lshlrev_b64 v[14:15], 10, v[14:15]
	v_lshl_add_u64 v[14:15], v[12:13], 0, v[14:15]
	global_load_dwordx4 v[80:83], v[10:11], off
	global_load_dwordx4 v[84:87], v[14:15], off
	v_add_u32_e32 v10, 0x600, v172
	v_ashrrev_i32_e32 v10, 5, v10
	v_add_u32_e32 v10, s17, v10
	v_ashrrev_i32_e32 v11, 31, v10
	v_lshlrev_b64 v[10:11], 10, v[10:11]
	v_lshl_add_u64 v[10:11], v[12:13], 0, v[10:11]
	global_load_dwordx4 v[88:91], v[10:11], off
	s_mov_b32 s35, 0x5040100
	s_waitcnt vmcnt(44)
	v_cvt_pk_bf16_f32 v10, v3, 0
	v_lshlrev_b32_e32 v11, 16, v10
	s_waitcnt vmcnt(42)
	v_cvt_pk_bf16_f32 v12, v5, 0
	v_lshlrev_b32_e32 v13, 16, v12
	s_waitcnt vmcnt(40)
	v_cvt_pk_bf16_f32 v14, v7, 0
	v_lshlrev_b32_e32 v15, 16, v14
	s_add_u32 s16, s6, 0x14000000
	s_addc_u32 s17, s7, 0
	s_add_u32 s18, s6, 0x3798900
	v_cvt_pk_bf16_f32 v64, v2, v3
	v_cvt_pk_bf16_f32 v65, v4, v5
	v_cvt_pk_bf16_f32 v66, v6, v7
	s_waitcnt vmcnt(38)
	v_cvt_pk_bf16_f32 v67, v8, v9
	s_addc_u32 s19, s7, 0
	s_lshl_b32 s36, s28, 1
	s_lshl_b32 s37, s31, 1
	s_movk_i32 s38, 0x220
	s_movk_i32 s39, 0x90
	v_mov_b32_e32 v173, 0x358637bd
	s_mov_b32 s40, 0x800000
	s_mov_b64 s[20:21], 0x17600400
	s_waitcnt vmcnt(28)
	v_perm_b32 v175, v23, v1, s35
	v_cvt_pk_bf16_f32 v1, v2, 0
	v_lshlrev_b32_e32 v10, 16, v1
	v_cvt_pk_bf16_f32 v1, v4, 0
	v_lshlrev_b32_e32 v12, 16, v1
	v_cvt_pk_bf16_f32 v1, v6, 0
	s_waitcnt vmcnt(27)
	v_perm_b32 v176, v24, v16, s35
	v_lshlrev_b32_e32 v14, 16, v1
	v_cvt_pk_bf16_f32 v1, v8, 0
	v_cvt_pk_bf16_f32 v16, v9, 0
	s_waitcnt vmcnt(26)
	v_perm_b32 v177, v25, v17, s35
	v_lshlrev_b32_e32 v17, 16, v16
	v_lshlrev_b32_e32 v16, 16, v1
	v_pk_add_f32 v[10:11], v[2:3], v[10:11] neg_lo:[0,1] neg_hi:[0,1]
	v_pk_add_f32 v[12:13], v[4:5], v[12:13] neg_lo:[0,1] neg_hi:[0,1]
	v_pk_add_f32 v[14:15], v[6:7], v[14:15] neg_lo:[0,1] neg_hi:[0,1]
	v_pk_add_f32 v[16:17], v[8:9], v[16:17] neg_lo:[0,1] neg_hi:[0,1]
	s_waitcnt vmcnt(25)
	v_perm_b32 v178, v26, v18, s35
	s_waitcnt vmcnt(24)
	v_perm_b32 v179, v27, v19, s35
	s_waitcnt vmcnt(23)
	v_perm_b32 v180, v28, v20, s35
	s_waitcnt vmcnt(22)
	v_perm_b32 v181, v29, v21, s35
	s_waitcnt vmcnt(21)
	v_perm_b32 v182, v30, v22, s35
	s_waitcnt vmcnt(12)
	v_perm_b32 v183, v39, v31, s35
	s_waitcnt vmcnt(11)
	v_perm_b32 v184, v40, v32, s35
	s_waitcnt vmcnt(10)
	v_perm_b32 v185, v41, v33, s35
	s_waitcnt vmcnt(9)
	v_perm_b32 v186, v42, v34, s35
	s_waitcnt vmcnt(8)
	v_perm_b32 v187, v43, v35, s35
	s_waitcnt vmcnt(7)
	v_perm_b32 v188, v44, v36, s35
	s_waitcnt vmcnt(6)
	v_perm_b32 v189, v45, v37, s35
	s_waitcnt vmcnt(5)
	v_perm_b32 v190, v46, v38, s35
	v_cvt_pk_bf16_f32 v68, v10, v11
	v_cvt_pk_bf16_f32 v69, v12, v13
	v_cvt_pk_bf16_f32 v70, v14, v15
	v_cvt_pk_bf16_f32 v71, v16, v17
	v_mov_b32_e32 v1, v0
	v_mov_b32_e32 v2, v0
	v_mov_b32_e32 v3, v0
	v_mov_b32_e32 v4, v0
	v_mov_b32_e32 v5, v0
	v_mov_b32_e32 v6, v0
	v_mov_b32_e32 v7, v0
	v_mov_b32_e32 v8, v0
	v_mov_b32_e32 v9, v0
	v_mov_b32_e32 v10, v0
	v_mov_b32_e32 v11, v0
	v_mov_b32_e32 v12, v0
	v_mov_b32_e32 v13, v0
	v_mov_b32_e32 v14, v0
	v_mov_b32_e32 v15, v0
	s_mov_b32 s41, 0x17600000
	v_mov_b32_e32 v174, 0x1200
	s_branch .LBB0_701
.LBB0_700:
	s_or_b64 exec, exec, s[4:5]
	v_lshlrev_b32_e32 v49, 6, v195
	v_or_b32_e32 v50, v49, v194
	v_lshlrev_b32_e32 v97, 2, v50
	s_waitcnt lgkmcnt(0)
	s_barrier
	global_load_dwordx4 v[50:53], v97, s[18:19]
	global_load_dwordx4 v[54:57], v97, s[18:19] offset:32
	v_lshlrev_b32_e32 v96, 5, v193
	v_bitop3_b32 v96, v96, 32, v191 bitop3:0x36
	v_lshl_add_u32 v96, v96, 2, 0
	ds_read_b32 v96, v96 offset:8192
	v_lshlrev_b64 v[58:59], 11, v[166:167]
	v_lshl_add_u64 v[58:59], s[6:7], 0, v[58:59]
	v_lshlrev_b32_e32 v148, 4, v192
	v_lshl_add_u64 v[58:59], v[162:163], 1, v[58:59]
	s_waitcnt lgkmcnt(0)
	v_add_f32_e32 v48, v48, v96
	v_fmamk_f32 v48, v48, 0x3c000000, v173
	v_lshl_add_u64 v[58:59], v[58:59], 0, v[148:149]
	v_lshlrev_b32_e32 v148, 1, v49
	v_mul_f32_e32 v49, 0x4b800000, v48
	v_cmp_gt_f32_e32 vcc, s40, v48
	v_lshlrev_b32_e32 v60, 16, v168
	v_and_b32_e32 v61, 0xffff0000, v168
	v_cndmask_b32_e32 v48, v48, v49, vcc
	v_rsq_f32_e32 v96, v48
	v_lshlrev_b32_e32 v62, 16, v169
	v_and_b32_e32 v63, 0xffff0000, v169
	v_lshlrev_b32_e32 v92, 16, v164
	v_mul_f32_e32 v98, 0x45800000, v96
	v_cndmask_b32_e32 v96, v96, v98, vcc
	v_pk_mul_f32 v[32:33], v[32:33], v[96:97] op_sel_hi:[1,0]
	v_pk_mul_f32 v[34:35], v[34:35], v[96:97] op_sel_hi:[1,0]
	v_pk_mul_f32 v[36:37], v[36:37], v[96:97] op_sel_hi:[1,0]
	v_pk_mul_f32 v[38:39], v[38:39], v[96:97] op_sel_hi:[1,0]
	v_and_b32_e32 v93, 0xffff0000, v164
	v_lshlrev_b32_e32 v94, 16, v165
	v_and_b32_e32 v95, 0xffff0000, v165
	v_lshl_add_u64 v[58:59], v[58:59], 0, v[148:149]
	v_add_co_u32_e64 v48, s[4:5], s41, v58
	v_pk_mul_f32 v[40:41], v[40:41], v[96:97] op_sel_hi:[1,0]
	s_nop 0
	v_addc_co_u32_e64 v49, s[4:5], 0, v59, s[4:5]
	v_pk_mul_f32 v[42:43], v[42:43], v[96:97] op_sel_hi:[1,0]
	v_pk_mul_f32 v[44:45], v[44:45], v[96:97] op_sel_hi:[1,0]
	v_pk_mul_f32 v[46:47], v[46:47], v[96:97] op_sel_hi:[1,0]
	v_pk_mul_f32 v[16:17], v[16:17], v[96:97] op_sel_hi:[1,0]
	v_pk_mul_f32 v[18:19], v[18:19], v[96:97] op_sel_hi:[1,0]
	v_pk_mul_f32 v[20:21], v[20:21], v[96:97] op_sel_hi:[1,0]
	v_pk_mul_f32 v[22:23], v[22:23], v[96:97] op_sel_hi:[1,0]
	v_pk_mul_f32 v[24:25], v[24:25], v[96:97] op_sel_hi:[1,0]
	v_pk_mul_f32 v[26:27], v[26:27], v[96:97] op_sel_hi:[1,0]
	v_pk_mul_f32 v[28:29], v[28:29], v[96:97] op_sel_hi:[1,0]
	v_pk_mul_f32 v[30:31], v[30:31], v[96:97] op_sel_hi:[1,0]
	s_sub_i32 s36, s36, s37
	s_andn2_b64 vcc, exec, s[26:27]
	s_mov_b32 s28, s42
	s_waitcnt vmcnt(1)
	v_pk_mul_f32 v[32:33], v[50:51], v[32:33]
	v_pk_mul_f32 v[34:35], v[52:53], v[34:35]
	s_waitcnt vmcnt(0)
	v_pk_mul_f32 v[36:37], v[54:55], v[36:37]
	v_pk_mul_f32 v[38:39], v[56:57], v[38:39]
	v_pk_mul_f32 v[32:33], v[32:33], v[60:61]
	v_pk_mul_f32 v[34:35], v[34:35], v[62:63]
	v_pk_mul_f32 v[36:37], v[36:37], v[92:93]
	v_pk_mul_f32 v[38:39], v[38:39], v[94:95]
	v_cvt_pk_bf16_f32 v32, v32, v33
	v_cvt_pk_bf16_f32 v33, v34, v35
	v_cvt_pk_bf16_f32 v34, v36, v37
	v_cvt_pk_bf16_f32 v35, v38, v39
	s_nop 0
	v_permlane32_swap_b32_e32 v32, v34
	v_permlane32_swap_b32_e32 v33, v35
	global_store_dwordx4 v[48:49], v[32:35], off offset:1024
	global_load_dwordx4 v[32:35], v97, s[18:19] offset:64
	s_nop 0
	global_load_dwordx4 v[36:39], v97, s[18:19] offset:96
	v_lshlrev_b32_e32 v48, 16, v160
	v_and_b32_e32 v49, 0xffff0000, v160
	v_lshlrev_b32_e32 v50, 16, v161
	v_and_b32_e32 v51, 0xffff0000, v161
	v_lshlrev_b32_e32 v52, 16, v158
	v_and_b32_e32 v53, 0xffff0000, v158
	v_lshlrev_b32_e32 v54, 16, v159
	v_and_b32_e32 v55, 0xffff0000, v159
	v_lshl_add_u64 v[56:57], v[58:59], 0, s[20:21]
	s_waitcnt vmcnt(1)
	v_pk_mul_f32 v[32:33], v[32:33], v[40:41]
	v_pk_mul_f32 v[34:35], v[34:35], v[42:43]
	s_waitcnt vmcnt(0)
	v_pk_mul_f32 v[36:37], v[36:37], v[44:45]
	v_pk_mul_f32 v[38:39], v[38:39], v[46:47]
	v_pk_mul_f32 v[32:33], v[32:33], v[48:49]
	v_pk_mul_f32 v[34:35], v[34:35], v[50:51]
	v_pk_mul_f32 v[36:37], v[36:37], v[52:53]
	v_pk_mul_f32 v[38:39], v[38:39], v[54:55]
	v_cvt_pk_bf16_f32 v32, v32, v33
	v_cvt_pk_bf16_f32 v33, v34, v35
	v_cvt_pk_bf16_f32 v34, v36, v37
	v_cvt_pk_bf16_f32 v35, v38, v39
	s_nop 0
	v_permlane32_swap_b32_e32 v32, v34
	v_permlane32_swap_b32_e32 v33, v35
	global_store_dwordx4 v[56:57], v[32:35], off offset:32
	global_load_dwordx4 v[32:35], v97, s[18:19] offset:128
	s_nop 0
	global_load_dwordx4 v[36:39], v97, s[18:19] offset:160
	v_lshlrev_b32_e32 v40, 16, v156
	v_and_b32_e32 v41, 0xffff0000, v156
	v_lshlrev_b32_e32 v42, 16, v157
	v_and_b32_e32 v43, 0xffff0000, v157
	v_lshlrev_b32_e32 v44, 16, v154
	v_and_b32_e32 v45, 0xffff0000, v154
	v_lshlrev_b32_e32 v46, 16, v155
	v_and_b32_e32 v47, 0xffff0000, v155
	s_waitcnt vmcnt(1)
	v_pk_mul_f32 v[16:17], v[16:17], v[32:33]
	v_pk_mul_f32 v[18:19], v[18:19], v[34:35]
	s_waitcnt vmcnt(0)
	v_pk_mul_f32 v[20:21], v[20:21], v[36:37]
	v_pk_mul_f32 v[22:23], v[22:23], v[38:39]
	v_pk_mul_f32 v[16:17], v[16:17], v[40:41]
	v_pk_mul_f32 v[18:19], v[18:19], v[42:43]
	v_pk_mul_f32 v[20:21], v[20:21], v[44:45]
	v_pk_mul_f32 v[22:23], v[22:23], v[46:47]
	v_cvt_pk_bf16_f32 v16, v16, v17
	v_cvt_pk_bf16_f32 v17, v18, v19
	v_cvt_pk_bf16_f32 v18, v20, v21
	v_cvt_pk_bf16_f32 v19, v22, v23
	s_nop 0
	v_permlane32_swap_b32_e32 v16, v18
	v_permlane32_swap_b32_e32 v17, v19
	global_store_dwordx4 v[56:57], v[16:19], off offset:64
	global_load_dwordx4 v[16:19], v97, s[18:19] offset:192
	s_nop 0
	global_load_dwordx4 v[20:23], v97, s[18:19] offset:224
	v_lshlrev_b32_e32 v32, 16, v152
	v_and_b32_e32 v33, 0xffff0000, v152
	v_lshlrev_b32_e32 v34, 16, v153
	v_and_b32_e32 v35, 0xffff0000, v153
	v_lshlrev_b32_e32 v36, 16, v150
	v_and_b32_e32 v37, 0xffff0000, v150
	v_lshlrev_b32_e32 v38, 16, v151
	v_and_b32_e32 v39, 0xffff0000, v151
	s_waitcnt vmcnt(1)
	v_pk_mul_f32 v[16:17], v[24:25], v[16:17]
	v_pk_mul_f32 v[18:19], v[26:27], v[18:19]
	s_waitcnt vmcnt(0)
	v_pk_mul_f32 v[20:21], v[28:29], v[20:21]
	v_pk_mul_f32 v[22:23], v[30:31], v[22:23]
	v_pk_mul_f32 v[16:17], v[16:17], v[32:33]
	v_pk_mul_f32 v[18:19], v[18:19], v[34:35]
	v_pk_mul_f32 v[20:21], v[20:21], v[36:37]
	v_pk_mul_f32 v[22:23], v[22:23], v[38:39]
	v_cvt_pk_bf16_f32 v16, v16, v17
	v_cvt_pk_bf16_f32 v17, v18, v19
	v_cvt_pk_bf16_f32 v18, v20, v21
	v_cvt_pk_bf16_f32 v19, v22, v23
	s_nop 0
	v_permlane32_swap_b32_e32 v16, v18
	v_permlane32_swap_b32_e32 v17, v19
	global_store_dwordx4 v[56:57], v[16:19], off offset:96
	s_barrier
	s_cbranch_vccz .LBB0_725

.LBB0_711:
	s_or_b64 exec, exec, s[4:5]
	ds_read_b32 v40, v40 offset:9984
	v_add_f32_e32 v37, v38, v37
	v_exp_f32_e64 v46, -v37
	v_and_b32_e32 v38, 0xffff0000, v175
	v_and_b32_e32 v123, 0xffff0000, v186
	s_waitcnt lgkmcnt(0)
	v_add_f32_e32 v40, v41, v40
	v_cndmask_b32_e32 v93, v40, v41, vcc
	v_and_b32_e32 v40, 0xfffff3f, v33
	v_mul_lo_u32 v142, v40, s39
	v_exp_f32_e32 v40, v37
	v_add_f32_e32 v37, v39, v37
	v_exp_f32_e32 v41, v37
	v_exp_f32_e64 v47, -v37
	v_and_b32_e32 v39, 0xffff0000, v176
	v_add_f32_e32 v37, v42, v37
	v_pk_mul_f32 v[94:95], v[40:41], v[38:39]
	v_lshlrev_b32_e32 v41, 16, v176
	v_lshlrev_b32_e32 v40, 16, v175
	v_pk_mul_f32 v[96:97], v[46:47], v[40:41]
	v_exp_f32_e32 v46, v37
	v_exp_f32_e64 v98, -v37
	v_add_f32_e32 v37, v43, v37
	v_exp_f32_e32 v47, v37
	v_exp_f32_e64 v99, -v37
	v_add_f32_e32 v37, v56, v37
	v_exp_f32_e32 v56, v37
	v_exp_f32_e64 v102, -v37
	v_add_f32_e32 v37, v57, v37
	v_exp_f32_e32 v57, v37
	v_exp_f32_e64 v103, -v37
	v_add_f32_e32 v37, v54, v37
	v_exp_f32_e32 v54, v37
	v_exp_f32_e64 v108, -v37
	v_add_f32_e32 v37, v55, v37
	v_exp_f32_e32 v55, v37
	v_exp_f32_e64 v109, -v37
	v_add_f32_e32 v37, v52, v37
	v_exp_f32_e32 v52, v37
	v_exp_f32_e64 v114, -v37
	v_add_f32_e32 v37, v53, v37
	v_exp_f32_e32 v53, v37
	v_exp_f32_e64 v115, -v37
	v_add_f32_e32 v37, v50, v37
	v_exp_f32_e32 v50, v37
	v_exp_f32_e64 v120, -v37
	v_add_f32_e32 v37, v51, v37
	v_exp_f32_e32 v51, v37
	v_and_b32_e32 v122, 0xffff0000, v185
	v_exp_f32_e64 v121, -v37
	v_add_f32_e32 v37, v48, v37
	v_pk_mul_f32 v[124:125], v[50:51], v[122:123]
	v_exp_f32_e32 v48, v37
	v_exp_f32_e64 v50, -v37
	v_add_f32_e32 v37, v49, v37
	v_exp_f32_e32 v49, v37
	v_and_b32_e32 v129, 0xffff0000, v188
	v_and_b32_e32 v128, 0xffff0000, v187
	v_exp_f32_e64 v51, -v37
	v_add_f32_e32 v37, v44, v37
	v_pk_mul_f32 v[130:131], v[48:49], v[128:129]
	v_exp_f32_e32 v44, v37
	v_exp_f32_e64 v48, -v37
	v_add_f32_e32 v37, v45, v37
	v_exp_f32_e32 v45, v37
	v_exp_f32_e64 v49, -v37
	v_and_b32_e32 v43, 0xffff0000, v178
	v_and_b32_e32 v42, 0xffff0000, v177
	v_and_b32_e32 v105, 0xffff0000, v180
	v_and_b32_e32 v104, 0xffff0000, v179
	v_and_b32_e32 v111, 0xffff0000, v182
	v_and_b32_e32 v110, 0xffff0000, v181
	v_lshlrev_b32_e32 v35, 5, v35
	v_pk_mul_f32 v[100:101], v[46:47], v[42:43]
	v_pk_mul_f32 v[56:57], v[56:57], v[104:105]
	v_pk_mul_f32 v[54:55], v[54:55], v[110:111]
	v_and_b32_e32 v117, 0xffff0000, v184
	v_and_b32_e32 v116, 0xffff0000, v183
	v_lshlrev_b32_e32 v133, 16, v188
	v_lshlrev_b32_e32 v132, 16, v187
	v_and_b32_e32 v137, 0xffff0000, v190
	v_and_b32_e32 v136, 0xffff0000, v189
	v_lshlrev_b32_e32 v139, 16, v190
	v_lshlrev_b32_e32 v138, 16, v189
	v_lshlrev_b32_e32 v47, 16, v178
	v_lshlrev_b32_e32 v46, 16, v177
	v_lshlrev_b32_e32 v107, 16, v180
	v_lshlrev_b32_e32 v106, 16, v179
	v_lshlrev_b32_e32 v113, 16, v182
	v_lshlrev_b32_e32 v112, 16, v181
	v_pk_mul_f32 v[52:53], v[52:53], v[116:117]
	v_pk_mul_f32 v[134:135], v[50:51], v[132:133]
	v_pk_mul_f32 v[44:45], v[44:45], v[136:137]
	v_pk_mul_f32 v[140:141], v[48:49], v[138:139]
	v_add3_u32 v35, 0, v142, v35
	v_cvt_pk_bf16_f32 v48, v94, v95
	v_cvt_pk_bf16_f32 v49, v100, v101
	v_cvt_pk_bf16_f32 v50, v56, v57
	v_cvt_pk_bf16_f32 v51, v54, v55
	v_pk_mul_f32 v[98:99], v[98:99], v[46:47]
	v_pk_mul_f32 v[102:103], v[102:103], v[106:107]
	v_pk_mul_f32 v[108:109], v[108:109], v[112:113]
	v_lshlrev_b32_e32 v119, 16, v184
	v_lshlrev_b32_e32 v118, 16, v183
	v_lshlrev_b32_e32 v127, 16, v186
	v_lshlrev_b32_e32 v126, 16, v185
	ds_write_b128 v35, v[48:51] offset:47104
	v_cvt_pk_bf16_f32 v48, v52, v53
	v_cvt_pk_bf16_f32 v49, v124, v125
	v_cvt_pk_bf16_f32 v50, v130, v131
	v_cvt_pk_bf16_f32 v51, v44, v45
	v_pk_mul_f32 v[114:115], v[114:115], v[118:119]
	v_pk_mul_f32 v[120:121], v[120:121], v[126:127]
	ds_write_b128 v35, v[48:51] offset:47120
	v_cvt_pk_bf16_f32 v48, v96, v97
	v_cvt_pk_bf16_f32 v49, v98, v99
	v_cvt_pk_bf16_f32 v50, v102, v103
	v_cvt_pk_bf16_f32 v51, v108, v109
	ds_write_b128 v35, v[48:51] offset:56320
	v_cvt_pk_bf16_f32 v48, v114, v115
	v_cvt_pk_bf16_f32 v49, v120, v121
	v_cvt_pk_bf16_f32 v50, v134, v135
	v_cvt_pk_bf16_f32 v51, v140, v141
	v_add_u32_e32 v37, 0xb800, v35
	ds_write_b128 v35, v[48:51] offset:56336
	v_add_f32_e32 v35, v31, v93
	v_exp_f32_e32 v31, v35
	v_exp_f32_e64 v45, -v35
	v_add_f32_e32 v35, v30, v35
	v_exp_f32_e32 v30, v35
	v_exp_f32_e64 v44, -v35
	v_add_f32_e32 v35, v29, v35
	v_exp_f32_e32 v29, v35
	v_exp_f32_e64 v49, -v35
	v_add_f32_e32 v35, v28, v35
	v_exp_f32_e32 v28, v35
	v_exp_f32_e64 v48, -v35
	v_add_f32_e32 v35, v27, v35
	v_exp_f32_e32 v27, v35
	v_exp_f32_e64 v51, -v35
	v_add_f32_e32 v35, v26, v35
	v_exp_f32_e32 v26, v35
	v_exp_f32_e64 v50, -v35
	v_add_f32_e32 v35, v25, v35
	v_exp_f32_e32 v25, v35
	v_exp_f32_e64 v53, -v35
	v_add_f32_e32 v35, v24, v35
	v_exp_f32_e32 v24, v35
	v_exp_f32_e64 v52, -v35
	v_add_f32_e32 v35, v23, v35
	v_exp_f32_e32 v23, v35
	v_exp_f32_e64 v55, -v35
	v_add_f32_e32 v35, v22, v35
	v_exp_f32_e32 v22, v35
	v_exp_f32_e64 v54, -v35
	v_add_f32_e32 v35, v21, v35
	v_exp_f32_e32 v21, v35
	v_exp_f32_e64 v57, -v35
	v_add_f32_e32 v35, v20, v35
	v_exp_f32_e32 v20, v35
	v_exp_f32_e64 v56, -v35
	v_add_f32_e32 v35, v19, v35
	v_exp_f32_e32 v19, v35
	v_exp_f32_e64 v95, -v35
	v_add_f32_e32 v35, v18, v35
	v_exp_f32_e32 v18, v35
	v_exp_f32_e64 v94, -v35
	v_add_f32_e32 v35, v17, v35
	v_exp_f32_e32 v17, v35
	v_exp_f32_e64 v97, -v35
	v_add_f32_e32 v35, v16, v35
	v_exp_f32_e32 v16, v35
	v_exp_f32_e64 v96, -v35
	s_sub_i32 s42, s28, s31
	v_pk_mul_f32 v[22:23], v[22:23], v[110:111]
	v_pk_mul_f32 v[20:21], v[20:21], v[104:105]
	v_pk_mul_f32 v[18:19], v[18:19], v[42:43]
	v_pk_mul_f32 v[16:17], v[16:17], v[38:39]
	s_cmp_lt_i32 s42, 0
	v_pk_mul_f32 v[30:31], v[30:31], v[136:137]
	v_pk_mul_f32 v[28:29], v[28:29], v[128:129]
	v_pk_mul_f32 v[26:27], v[26:27], v[122:123]
	v_pk_mul_f32 v[24:25], v[24:25], v[116:117]
	v_cvt_pk_bf16_f32 v16, v16, v17
	v_cvt_pk_bf16_f32 v17, v18, v19
	v_cvt_pk_bf16_f32 v18, v20, v21
	v_cvt_pk_bf16_f32 v19, v22, v23
	s_cselect_b64 s[26:27], -1, 0
	s_cmp_gt_i32 s42, -1
	v_pk_mul_f32 v[54:55], v[54:55], v[112:113]
	v_pk_mul_f32 v[56:57], v[56:57], v[106:107]
	v_pk_mul_f32 v[42:43], v[94:95], v[46:47]
	v_pk_mul_f32 v[38:39], v[96:97], v[40:41]
	ds_write_b128 v37, v[16:19] offset:18432
	v_cvt_pk_bf16_f32 v16, v24, v25
	v_cvt_pk_bf16_f32 v17, v26, v27
	v_cvt_pk_bf16_f32 v18, v28, v29
	v_cvt_pk_bf16_f32 v19, v30, v31
	s_cselect_b32 s4, s42, -1
	v_pk_mul_f32 v[44:45], v[44:45], v[138:139]
	v_pk_mul_f32 v[48:49], v[48:49], v[132:133]
	v_pk_mul_f32 v[50:51], v[50:51], v[126:127]
	v_pk_mul_f32 v[52:53], v[52:53], v[118:119]
	ds_write_b128 v37, v[16:19] offset:18448
	v_cvt_pk_bf16_f32 v16, v38, v39
	v_cvt_pk_bf16_f32 v17, v42, v43
	v_cvt_pk_bf16_f32 v18, v56, v57
	v_cvt_pk_bf16_f32 v19, v54, v55
	v_lshrrev_b32_e32 v92, 2, v33
	ds_write_b128 v37, v[16:19] offset:27648
	v_cvt_pk_bf16_f32 v16, v52, v53
	v_cvt_pk_bf16_f32 v17, v50, v51
	v_cvt_pk_bf16_f32 v18, v48, v49
	v_cvt_pk_bf16_f32 v19, v44, v45
	s_cmp_lt_i32 s4, 0
	ds_write_b128 v37, v[16:19] offset:27664
	s_waitcnt lgkmcnt(0)
	s_barrier
	s_cbranch_scc1 .LBB0_713
	v_ashrrev_i32_e32 v16, 2, v33
	s_and_b32 s5, s4, 1
	s_lshl_b32 s4, s4, 5
	v_and_b32_e32 v16, 0xffffffc0, v16
	s_and_b32 s29, s4, 0x7fffffc0
	v_lshl_add_u32 v16, s5, 7, v16
	v_or_b32_e32 v16, v16, v197
	v_and_or_b32 v148, v92, 48, s29
	v_lshlrev_b64 v[18:19], 9, v[148:149]
	v_ashrrev_i32_e32 v17, 31, v16
	v_lshl_add_u64 v[20:21], s[12:13], 0, v[18:19]
	v_lshlrev_b64 v[16:17], 1, v[16:17]
	v_lshl_add_u64 v[20:21], v[20:21], 0, v[16:17]
	v_lshl_add_u64 v[18:19], s[10:11], 0, v[18:19]
	v_lshl_add_u64 v[16:17], v[18:19], 0, v[16:17]
	v_add_co_u32_e32 v18, vcc, s30, v20
	global_load_ushort v22, v[20:21], off
	global_load_ushort v23, v[20:21], off offset:512
	global_load_ushort v24, v[20:21], off offset:1024
	global_load_ushort v25, v[20:21], off offset:1536
	global_load_ushort v26, v[20:21], off offset:2048
	global_load_ushort v27, v[20:21], off offset:2560
	global_load_ushort v28, v[20:21], off offset:3072
	global_load_ushort v29, v[20:21], off offset:3584
	global_load_ushort v30, v[16:17], off
	global_load_ushort v31, v[16:17], off offset:512
	global_load_ushort v38, v[16:17], off offset:1024
	global_load_ushort v39, v[16:17], off offset:1536
	global_load_ushort v40, v[16:17], off offset:2048
	global_load_ushort v41, v[16:17], off offset:2560
	global_load_ushort v42, v[16:17], off offset:3072
	global_load_ushort v43, v[16:17], off offset:3584
	v_addc_co_u32_e32 v19, vcc, 0, v21, vcc
	v_add_co_u32_e32 v16, vcc, s30, v16
	s_lshl_b32 s4, s5, 9
	s_nop 0
	v_addc_co_u32_e32 v17, vcc, 0, v17, vcc
	global_load_ushort v44, v[18:19], off
	global_load_ushort v45, v[18:19], off offset:512
	global_load_ushort v46, v[18:19], off offset:1024
	global_load_ushort v47, v[18:19], off offset:1536
	global_load_ushort v48, v[18:19], off offset:2048
	global_load_ushort v49, v[18:19], off offset:2560
	global_load_ushort v50, v[18:19], off offset:3072
	global_load_ushort v51, v[18:19], off offset:3584
	global_load_ushort v52, v[16:17], off
	global_load_ushort v53, v[16:17], off offset:512
	global_load_ushort v54, v[16:17], off offset:1024
	global_load_ushort v55, v[16:17], off offset:1536
	global_load_ushort v56, v[16:17], off offset:2048
	global_load_ushort v57, v[16:17], off offset:2560
	global_load_ushort v93, v[16:17], off offset:3072
	global_load_ushort v94, v[16:17], off offset:3584
	v_ashrrev_i32_e32 v16, 3, v33
	v_add_u32_e32 v16, s29, v16
	v_ashrrev_i32_e32 v17, 31, v16
	v_lshlrev_b64 v[16:17], 7, v[16:17]
	s_add_u32 s4, s33, s4
	v_add_u32_e32 v20, s29, v62
	v_lshl_add_u64 v[16:17], s[14:15], 0, v[16:17]
	v_mov_b32_e32 v37, v149
	s_addc_u32 s5, s34, 0
	v_mov_b32_e32 v35, v149
	v_ashrrev_i32_e32 v21, 31, v20
	v_lshl_add_u64 v[16:17], v[16:17], 0, v[36:37]
	v_lshl_add_u64 v[18:19], s[4:5], 0, v[34:35]
	v_lshlrev_b64 v[20:21], 10, v[20:21]
	v_lshl_add_u64 v[20:21], v[18:19], 0, v[20:21]
	global_load_dwordx4 v[72:75], v[16:17], off
	global_load_dwordx4 v[76:79], v[20:21], off
	v_add_u32_e32 v16, s29, v61
	v_ashrrev_i32_e32 v17, 31, v16
	v_add_u32_e32 v20, s29, v60
	v_lshlrev_b64 v[16:17], 10, v[16:17]
	v_ashrrev_i32_e32 v21, 31, v20
	v_lshl_add_u64 v[16:17], v[18:19], 0, v[16:17]
	v_lshlrev_b64 v[20:21], 10, v[20:21]
	v_lshl_add_u64 v[20:21], v[18:19], 0, v[20:21]
	global_load_dwordx4 v[80:83], v[16:17], off
	global_load_dwordx4 v[84:87], v[20:21], off
	v_add_u32_e32 v16, s29, v59
	v_ashrrev_i32_e32 v17, 31, v16
	v_lshlrev_b64 v[16:17], 10, v[16:17]
	v_lshl_add_u64 v[16:17], v[18:19], 0, v[16:17]
	global_load_dwordx4 v[88:91], v[16:17], off
	s_waitcnt vmcnt(28)
	v_perm_b32 v175, v30, v22, s35
	s_waitcnt vmcnt(27)
	v_perm_b32 v176, v31, v23, s35
	s_waitcnt vmcnt(26)
	v_perm_b32 v177, v38, v24, s35
	s_waitcnt vmcnt(25)
	v_perm_b32 v178, v39, v25, s35
	s_waitcnt vmcnt(24)
	v_perm_b32 v179, v40, v26, s35
	s_waitcnt vmcnt(23)
	v_perm_b32 v180, v41, v27, s35
	s_waitcnt vmcnt(22)
	v_perm_b32 v181, v42, v28, s35
	s_waitcnt vmcnt(21)
	v_perm_b32 v182, v43, v29, s35
	s_waitcnt vmcnt(12)
	v_perm_b32 v183, v52, v44, s35
	s_waitcnt vmcnt(11)
	v_perm_b32 v184, v53, v45, s35
	s_waitcnt vmcnt(10)
	v_perm_b32 v185, v54, v46, s35
	s_waitcnt vmcnt(9)
	v_perm_b32 v186, v55, v47, s35
	s_waitcnt vmcnt(8)
	v_perm_b32 v187, v56, v48, s35
	s_waitcnt vmcnt(7)
	v_perm_b32 v188, v57, v49, s35
	s_waitcnt vmcnt(6)
	v_perm_b32 v189, v93, v50, s35
	s_waitcnt vmcnt(5)
	v_perm_b32 v190, v94, v51, s35
